# MLA loop: one barrier per key tile, plus a workgroup barrier after the post-loop PV so the next unit's prologue cannot restage the LDS ring under a late reader (race fix)
# baseline (speedup 1.0000x reference)
.Lmla_endY:
.Lmla_store:
	s_and_b64 vcc, exec, s[22:23]
	s_cbranch_vccz .Lmla_nostk
	s_and_b32 s24, s100, 0xffff
	v_add3_u32 v159, s24, v170, v171
	s_waitcnt vmcnt(1)
	ds_write_b128 v159, v[90:93]
	s_and_saveexec_b64 s[22:23], s[38:39]
	s_cbranch_execz .Lmla_k1st
	v_add3_u32 v159, s24, v174, v191
	ds_write_b128 v159, v[94:97]

; template <int MODE> DI void attn_unit(int b, int qb, const bf16* Qb, int qpitch, const bf16* Kb, int kpitch, const bf16* VT, bf16* O, float* ssq, ...
;     ...
;         buf ^= 1;
;     }
;     ...
;     lsum += __shfl_xor(lsum, 32);
.Lmla_nopv2:
	s_barrier
